# safety: staged LDS-DMA pieces guaranteed landed before the DF exchange barrier again (counted per role: vmcnt 0 / 16 / 17), as the original WAIT_BAR(0) did
# baseline (speedup 1.0000x reference)
.LBB0_451:
	s_mov_b32 s95, 0
	v_mbcnt_lo_u32_b32 v0, -1, 0
	v_mbcnt_hi_u32_b32 v0, -1, v0
	v_readlane_b32 s2, v254, 2
	v_sub_u32_e32 v0, 0, v0
	v_mov_b32_e32 v95, 0xf0000
	v_cmp_eq_u32_e32 vcc, s2, v0
	s_and_saveexec_b64 s[2:3], vcc
	s_cbranch_execz .LBB0_456
	v_mov_b32_e32 v0, s69
	ds_read_b32 v0, v0
	v_readlane_b32 s5, v254, 32
	v_readlane_b32 s8, v254, 34
	v_mov_b32_e32 v95, 0xf0000
	s_waitcnt lgkmcnt(0)
	v_readfirstlane_b32 s4, v0
	s_and_b32 s5, s4, s5
	s_cmp_eq_u32 s5, 0
	v_readlane_b32 s5, v254, 31
	s_cselect_b32 s5, s5, 15
	s_and_b32 s8, s4, s8
	s_cmp_eq_u32 s8, 0
	v_readlane_b32 s8, v254, 33
	s_cselect_b32 s5, s8, s5
	v_readlane_b32 s8, v254, 36
	s_and_b32 s8, s4, s8
	s_cmp_eq_u32 s8, 0
	v_readlane_b32 s8, v254, 35
	s_cselect_b32 s5, s8, s5
	v_readlane_b32 s8, v254, 38
	s_and_b32 s8, s4, s8
	s_cmp_eq_u32 s8, 0
	v_readlane_b32 s8, v254, 37
	s_cselect_b32 s5, s8, s5
	v_readlane_b32 s8, v254, 40
	s_and_b32 s8, s4, s8
	s_cmp_eq_u32 s8, 0
	v_readlane_b32 s8, v254, 39
	s_cselect_b32 s5, s8, s5
	v_readlane_b32 s8, v254, 42
	s_and_b32 s8, s4, s8
	s_cmp_eq_u32 s8, 0
	v_readlane_b32 s8, v254, 41
	s_cselect_b32 s5, s8, s5
	v_readlane_b32 s8, v254, 44
	s_and_b32 s8, s4, s8
	s_cmp_eq_u32 s8, 0
	v_readlane_b32 s8, v254, 43
	s_cselect_b32 s5, s8, s5
	v_readlane_b32 s8, v254, 46
	s_and_b32 s8, s4, s8
	s_cmp_eq_u32 s8, 0
	v_readlane_b32 s8, v254, 45
	s_cselect_b32 s5, s8, s5
	s_bitcmp0_b32 s4, 8
	s_cselect_b32 s4, 8, 15
	s_cmp_eq_u32 s5, 15
	s_cselect_b32 s10, s4, s5
	s_cmp_eq_u32 s10, 15
	s_cbranch_scc1 .LBB0_456
	s_mov_b64 s[8:9], exec
	v_mbcnt_lo_u32_b32 v0, s8, 0
	v_mbcnt_hi_u32_b32 v0, s9, v0
	v_cmp_eq_u32_e32 vcc, 0, v0
	s_and_saveexec_b64 s[4:5], vcc
	s_cbranch_execz .LBB0_455
	s_lshl_b32 s11, s10, 6
	s_add_i32 s11, s11, 64
	s_cmp_lt_u32 s10, 8
	s_cselect_b32 s80, s11, 0
	s_lshl_b64 s[12:13], s[80:81], 2
	v_readlane_b32 s14, v254, 51
	v_readlane_b32 s15, v254, 52
	s_add_u32 s12, s14, s12
	s_addc_u32 s13, s15, s13
	s_bcnt1_i32_b64 s8, s[8:9]
	v_mov_b32_e32 v253, s8
	global_atomic_add v253, v1, v253, s[12:13] sc0
	s_mov_b32 s95, 1

.LBB0_458:
	v_readlane_b32 s2, v255, 27
	s_cmp_gt_u32 s63, 3
	s_cbranch_scc1 .Ldf_w_c1
	s_cmp_lg_u32 s95, 0
	s_cbranch_scc1 .Ldf_w_cl
	s_waitcnt vmcnt(16)
	s_branch .Ldf_w_done
.Ldf_w_cl:
	s_waitcnt vmcnt(17)
	s_branch .Ldf_w_done

.Ldf_w_done:
	s_waitcnt lgkmcnt(0)
	s_barrier
	v_readlane_b32 s3, v255, 28
	s_andn2_b64 vcc, exec, s[2:3]
	v_readlane_b32 s2, v255, 25
	s_nop 1
	v_lshl_add_u32 v0, v216, 2, s2
	s_cbranch_vccnz .LBB0_460
	v_readlane_b32 s2, v255, 31
	v_mov_b32_e32 v3, v217
	v_mov_b32_e32 v4, v217
	v_mov_b32_e32 v2, s2
	ds_read_b32 v2, v2
	v_permlane32_swap_b32_e32 v3, v4
	v_add_f32_e32 v3, v3, v4
	s_waitcnt lgkmcnt(0)
	v_div_scale_f32 v4, s[2:3], v3, v3, v2
	v_rcp_f32_e32 v5, v4
	s_nop 0
	v_fma_f32 v6, -v4, v5, 1.0
	v_fmac_f32_e32 v5, v6, v5
	v_div_scale_f32 v6, vcc, v2, v3, v2
	v_mul_f32_e32 v7, v6, v5
	v_fma_f32 v8, -v4, v7, v6
	v_fmac_f32_e32 v7, v8, v5
	v_fma_f32 v4, -v4, v7, v6
	v_div_fmas_f32 v4, v4, v5, v7
	v_div_fixup_f32 v2, v4, v3, v2
	v_mul_f32_e32 v3, v64, v2
	v_mul_f32_e32 v4, v65, v2
	ds_write2st64_b32 v0, v3, v4 offset1:1
	v_mul_f32_e32 v3, v66, v2
	v_mul_f32_e32 v4, v67, v2
	ds_write2st64_b32 v0, v3, v4 offset0:2 offset1:3
	v_mul_f32_e32 v3, v68, v2
	v_mul_f32_e32 v4, v69, v2
	ds_write2st64_b32 v0, v3, v4 offset0:4 offset1:5
	v_mul_f32_e32 v3, v70, v2
	v_mul_f32_e32 v4, v71, v2
	ds_write2st64_b32 v0, v3, v4 offset0:6 offset1:7
	v_mul_f32_e32 v3, v72, v2
	v_mul_f32_e32 v4, v73, v2
	ds_write2st64_b32 v0, v3, v4 offset0:8 offset1:9
	v_mul_f32_e32 v3, v74, v2
	v_mul_f32_e32 v4, v75, v2
	ds_write2st64_b32 v0, v3, v4 offset0:10 offset1:11
	v_mul_f32_e32 v3, v76, v2
	v_mul_f32_e32 v4, v77, v2
	ds_write2st64_b32 v0, v3, v4 offset0:12 offset1:13
	v_mul_f32_e32 v3, v78, v2
	v_mul_f32_e32 v4, v79, v2
	ds_write2st64_b32 v0, v3, v4 offset0:14 offset1:15
	v_mul_f32_e32 v3, v48, v2
	v_mul_f32_e32 v4, v49, v2
	ds_write2st64_b32 v0, v3, v4 offset0:16 offset1:17
	v_mul_f32_e32 v3, v50, v2
	v_mul_f32_e32 v4, v51, v2
	ds_write2st64_b32 v0, v3, v4 offset0:18 offset1:19
	v_mul_f32_e32 v3, v52, v2
	v_mul_f32_e32 v4, v53, v2
	ds_write2st64_b32 v0, v3, v4 offset0:20 offset1:21
	v_mul_f32_e32 v3, v54, v2
	v_mul_f32_e32 v4, v55, v2
	ds_write2st64_b32 v0, v3, v4 offset0:22 offset1:23
	v_mul_f32_e32 v3, v56, v2
	v_mul_f32_e32 v4, v57, v2
	ds_write2st64_b32 v0, v3, v4 offset0:24 offset1:25
	v_mul_f32_e32 v3, v58, v2
	v_mul_f32_e32 v4, v59, v2
	ds_write2st64_b32 v0, v3, v4 offset0:26 offset1:27
	v_mul_f32_e32 v3, v60, v2
	v_mul_f32_e32 v4, v61, v2
	ds_write2st64_b32 v0, v3, v4 offset0:28 offset1:29
	v_mul_f32_e32 v3, v62, v2
	v_mul_f32_e32 v4, v63, v2
	ds_write2st64_b32 v0, v3, v4 offset0:30 offset1:31
	v_mul_f32_e32 v3, v32, v2
	v_mul_f32_e32 v4, v33, v2
	ds_write2st64_b32 v0, v3, v4 offset0:32 offset1:33
	v_mul_f32_e32 v3, v34, v2
	v_mul_f32_e32 v4, v35, v2
	ds_write2st64_b32 v0, v3, v4 offset0:34 offset1:35
	v_mul_f32_e32 v3, v36, v2
	v_mul_f32_e32 v4, v37, v2
	ds_write2st64_b32 v0, v3, v4 offset0:36 offset1:37
	v_mul_f32_e32 v3, v38, v2
	v_mul_f32_e32 v4, v39, v2
	ds_write2st64_b32 v0, v3, v4 offset0:38 offset1:39
	v_mul_f32_e32 v3, v40, v2
	v_mul_f32_e32 v4, v41, v2
	ds_write2st64_b32 v0, v3, v4 offset0:40 offset1:41
	v_mul_f32_e32 v3, v42, v2
	v_mul_f32_e32 v4, v43, v2
	ds_write2st64_b32 v0, v3, v4 offset0:42 offset1:43
	v_mul_f32_e32 v3, v44, v2
	v_mul_f32_e32 v4, v45, v2
	ds_write2st64_b32 v0, v3, v4 offset0:44 offset1:45
	v_mul_f32_e32 v3, v46, v2
	v_mul_f32_e32 v4, v47, v2
	ds_write2st64_b32 v0, v3, v4 offset0:46 offset1:47
	v_mul_f32_e32 v3, v16, v2
	v_mul_f32_e32 v4, v17, v2
	ds_write2st64_b32 v0, v3, v4 offset0:48 offset1:49
	v_mul_f32_e32 v3, v18, v2
	v_mul_f32_e32 v4, v19, v2
	ds_write2st64_b32 v0, v3, v4 offset0:50 offset1:51
	v_mul_f32_e32 v3, v20, v2
	v_mul_f32_e32 v4, v21, v2
	ds_write2st64_b32 v0, v3, v4 offset0:52 offset1:53
	v_mul_f32_e32 v3, v22, v2
	v_mul_f32_e32 v4, v23, v2
	ds_write2st64_b32 v0, v3, v4 offset0:54 offset1:55
	v_mul_f32_e32 v3, v24, v2
	v_mul_f32_e32 v4, v25, v2
	ds_write2st64_b32 v0, v3, v4 offset0:56 offset1:57
	v_mul_f32_e32 v3, v26, v2
	v_mul_f32_e32 v4, v27, v2
	ds_write2st64_b32 v0, v3, v4 offset0:58 offset1:59
	v_mul_f32_e32 v3, v28, v2
	v_mul_f32_e32 v4, v29, v2
	ds_write2st64_b32 v0, v3, v4 offset0:60 offset1:61
	v_mul_f32_e32 v3, v30, v2
	v_mul_f32_e32 v2, v31, v2
	ds_write2st64_b32 v0, v3, v2 offset0:62 offset1:63
